# NSA phase: the eight heaviest attention workgroups of each XCD group no longer poll their group's extras queue after their item
# speedup vs baseline: 1.0024x; 1.0024x over previous
; DEVI int vhalf() { int t = threadIdx.x >> 8; t = __builtin_amdgcn_readfirstlane(t); return t; }
; DEVI int vblk() { return (int)blockIdx.x * 2 + vhalf(); }
; DEVI int vgrid() { return (int)gridDim.x * 2; }
; DEVI void pull_extras(const Params& p, int l, char* lds, volatile int* nsa_cnt, int max_pulls) {
;   unsigned* q = (unsigned*)(p.ws + OFF_BAR) + 3500 + l;
;   for (int n = 0; n < max_pulls; ++n) {
;     __syncthreads();
;     if (threadIdx.x == 0) nsa_cnt[2] = (int)atomicAdd(q, 2u);
;     __syncthreads();
;     const int base = nsa_cnt[2];
;     if (base >= P3B_EXTRA) break;
;     int i = base + vhalf();
;     if (i < P3_GMLP) { gmlp_item(p, l, i, lds); continue; }
;     i -= P3_GMLP;
;     if (i < P3_CONF) { conf_item(p, l, i, lds); continue; }
;     i -= P3_CONF;
;     sconv_item(p, l, i);
;   }
; }
; DEVI void phase3b(const Params& p, int l, char* lds, volatile int* nsa_cnt) {
;   for (int item = vblk(); item < 512; item += vgrid()) nsa_item(p, l, item, lds, nsa_cnt);
;   pull_extras(p, l, lds, nsa_cnt, 1 << 30);
.LBB0_527:
	v_readlane_b32 s0, v243, 13
	s_cmp_lt_u32 s0, 0x80
	s_cbranch_scc1 .Lp3b_done
	v_readlane_b32 s0, v242, 43
	v_readlane_b32 s1, v242, 44
	s_mov_b32 s36, s0
	s_ashr_i32 s37, s0, 31
	s_lshl_b64 s[0:1], s[36:37], 2
	v_readlane_b32 s4, v243, 22
	s_add_u32 s0, s4, s0
	v_readlane_b32 s4, v243, 23
	s_addc_u32 s1, s4, s1
	s_mul_i32 s4, s36, 28
	v_readlane_b32 s5, v243, 13
	s_bfe_u32 s5, s5, 0x30001
	s_lshl_b32 s5, s5, 2
	s_add_i32 s4, s4, s5
	s_add_i32 s4, s4, 16
	s_add_u32 s0, s0, s4
	s_addc_u32 s1, s1, 0
	s_mul_hi_i32 s20, s36, 0xc00
	s_mul_i32 s23, s36, 0xc00
	s_mul_hi_i32 s25, s36, 0x7c00
	s_mul_i32 s27, s36, 0x7c00
	s_lshl_b32 s4, s36, 8
	s_mov_b32 s28, s36
	s_lshl_b32 s30, s36, 2
	v_readlane_b32 s36, v244, 35
	s_ashr_i32 s5, s4, 31
	v_readlane_b32 s38, v244, 37
	v_readlane_b32 s40, v244, 39
	v_readlane_b32 s41, v244, 40
	v_readlane_b32 s42, v244, 41
	v_readlane_b32 s43, v244, 42
	v_readlane_b32 s44, v244, 43
	v_readlane_b32 s45, v244, 44
	v_readlane_b32 s46, v244, 45
	v_readlane_b32 s47, v244, 46
	v_readlane_b32 s48, v244, 47
	v_readlane_b32 s49, v244, 48
	v_readlane_b32 s50, v244, 49
	v_readlane_b32 s51, v244, 50
	v_readlane_b32 s37, v244, 36
	v_readlane_b32 s39, v244, 38
	s_add_u32 s38, s36, s23
	v_readlane_b32 s40, v244, 19
	s_addc_u32 s39, s37, s20
	v_readlane_b32 s48, v244, 27
	v_writelane_b32 v242, s28, 43
	v_readlane_b32 s41, v244, 20
	v_readlane_b32 s49, v244, 28
	s_add_u32 s40, s48, s27
	v_writelane_b32 v242, s29, 44
	v_readlane_b32 s42, v244, 21
	v_readlane_b32 s52, v244, 31
	s_addc_u32 s41, s49, s25
	s_lshl_b64 s[28:29], s[4:5], 2
	v_readlane_b32 s43, v244, 22
	v_readlane_b32 s53, v244, 32
	s_add_u32 s42, s52, s28
	v_readlane_b32 s44, v244, 23
	v_readlane_b32 s54, v244, 33
	s_addc_u32 s43, s53, s29
	v_readlane_b32 s45, v244, 24
	v_readlane_b32 s50, v244, 29
	v_readlane_b32 s51, v244, 30
	v_readlane_b32 s55, v244, 34
	s_add_u32 s44, s54, s28
	s_addc_u32 s45, s55, s29
	v_readlane_b32 s48, v244, 3
	v_readlane_b32 s46, v244, 25
	v_readlane_b32 s54, v244, 9
	v_readlane_b32 s47, v244, 26
	v_readlane_b32 s55, v244, 10
	s_add_u32 s46, s54, s28
	v_readlane_b32 s56, v244, 11
	s_addc_u32 s47, s55, s29
	v_readlane_b32 s49, v244, 4
	v_readlane_b32 s50, v244, 5
	v_readlane_b32 s51, v244, 6
	v_readlane_b32 s57, v244, 12
	v_readlane_b32 s62, v244, 17
	v_readlane_b32 s63, v244, 18
	s_add_u32 s48, s56, s28
	s_addc_u32 s49, s57, s29
	s_add_i32 s5, s26, 0x7c00
	s_add_i32 s62, s26, 0x4400
	s_mov_b32 s63, 0
	s_mov_b64 s[50:51], 0
	s_movk_i32 s11, 0x500
	s_movk_i32 s23, 0x1000
	v_readlane_b32 s52, v244, 7
	v_readlane_b32 s53, v244, 8
	v_readlane_b32 s58, v244, 13
	v_readlane_b32 s59, v244, 14
	v_readlane_b32 s60, v244, 15
	v_readlane_b32 s61, v244, 16
	s_branch .LBB0_529

; DEVI int vblk() { return (int)blockIdx.x * 2 + vhalf(); }
; DEVI int vgrid() { return (int)gridDim.x * 2; }
; DEVI void phase3b(const Params& p, int l, char* lds, volatile int* nsa_cnt) {
;   for (int item = vblk(); item < 512; item += vgrid()) nsa_item(p, l, item, lds, nsa_cnt);
;   pull_extras(p, l, lds, nsa_cnt, 1 << 30);
; }
.LBB0_600:
	s_or_b64 exec, exec, s[50:51]
.Lp3b_done:
	s_mov_b64 s[0:1], 0
.LBB0_601:
	s_and_b64 vcc, exec, s[0:1]
	s_cbranch_vccz .LBB0_670
	v_readlane_b32 s0, v244, 57
	v_readlane_b32 s1, v244, 58
	s_load_dword s27, s[0:1], 0x0
	v_readlane_b32 s0, v243, 24
	v_readlane_b32 s1, v243, 25
	v_readfirstlane_b32 s29, v220
	s_andn2_b64 vcc, exec, s[0:1]
	s_mov_b64 s[0:1], -1
	s_cbranch_vccnz .LBB0_657
	v_readlane_b32 s0, v242, 43
	v_readlane_b32 s1, v242, 44
	s_mul_i32 s0, s0, 3
	s_ashr_i32 s1, s0, 31
	s_lshl_b64 s[0:1], s[0:1], 8
	v_readlane_b32 s36, v244, 19
	v_readlane_b32 s37, v244, 20
	v_readlane_b32 s42, v244, 25
	v_readlane_b32 s45, v244, 28
	s_add_u32 s4, s36, s0
	v_readlane_b32 s0, v244, 0
	s_addc_u32 s5, s37, s1
	s_waitcnt lgkmcnt(0)
	s_lshl_b32 s52, s27, 13
	v_readlane_b32 s53, v242, 36
	s_and_b32 s42, s0, 7
	s_lshl_b32 s42, s42, 1
	s_bfe_u32 s28, s0, 0x10003
	s_or_b32 s42, s42, s28
	s_bfe_u32 s28, s0, 0x10004
	s_lshl_b32 s28, s28, 4
	s_or_b32 s42, s42, s28
	s_lshl_b32 s53, s42, 13
	v_readlane_b32 s28, v243, 26
	v_readlane_b32 s45, v243, 27
	v_readlane_b32 s38, v244, 21
	v_readlane_b32 s39, v244, 22
	v_readlane_b32 s40, v244, 23
	v_readlane_b32 s41, v244, 24
	v_readlane_b32 s43, v244, 26
	v_readlane_b32 s44, v244, 27
	v_readlane_b32 s46, v244, 29
	v_readlane_b32 s47, v244, 30
	v_readlane_b32 s48, v244, 31
	v_readlane_b32 s49, v244, 32
	v_readlane_b32 s50, v244, 33
	v_readlane_b32 s51, v244, 34
	s_branch .LBB0_606
